# interleave the 32 serial half-wave reductions of the residual-GEMM epilogue (15 chains side by side)
# speedup vs baseline: 1.0356x; 1.0103x over previous
.LBB0_265:
	s_or_b64 exec, exec, s[10:11]
	v_mul_f32_e32 v168, v168, v168
	v_fmac_f32_e32 v168, v167, v167
	v_mul_f32_e32 v166, v166, v166
	v_fmac_f32_e32 v166, v165, v165
	v_mul_f32_e32 v164, v164, v164
	v_fmac_f32_e32 v164, v163, v163
	v_mul_f32_e32 v162, v162, v162
	v_fmac_f32_e32 v162, v161, v161
	v_mul_f32_e32 v159, v159, v159
	v_fmac_f32_e32 v159, v157, v157
	v_mul_f32_e32 v158, v158, v158
	v_fmac_f32_e32 v158, v156, v156
	v_mul_f32_e32 v152, v152, v152
	v_fmac_f32_e32 v152, v150, v150
	v_mul_f32_e32 v160, v160, v160
	v_fmac_f32_e32 v160, v149, v149
	v_mul_f32_e32 v153, v153, v153
	v_fmac_f32_e32 v153, v151, v151
	v_mul_f32_e32 v155, v155, v155
	v_fmac_f32_e32 v155, v154, v154
	v_mul_f32_e32 v148, v148, v148
	v_fmac_f32_e32 v148, v147, v147
	v_mul_f32_e32 v146, v146, v146
	v_fmac_f32_e32 v146, v145, v145
	v_mul_f32_e32 v142, v142, v142
	v_fmac_f32_e32 v142, v141, v141
	v_mul_f32_e32 v144, v144, v144
	v_fmac_f32_e32 v144, v143, v143
	v_mul_f32_e32 v140, v140, v140
	v_fmac_f32_e32 v140, v139, v139
	s_waitcnt lgkmcnt(0)
	ds_bpermute_b32 v167, v109, v168
	ds_bpermute_b32 v165, v109, v166
	ds_bpermute_b32 v163, v109, v164
	ds_bpermute_b32 v161, v109, v162
	ds_bpermute_b32 v157, v109, v159
	ds_bpermute_b32 v156, v109, v158
	ds_bpermute_b32 v150, v109, v152
	ds_bpermute_b32 v149, v109, v160
	ds_bpermute_b32 v151, v109, v153
	ds_bpermute_b32 v154, v109, v155
	ds_bpermute_b32 v147, v109, v148
	ds_bpermute_b32 v145, v109, v146
	ds_bpermute_b32 v141, v109, v142
	ds_bpermute_b32 v143, v109, v144
	ds_bpermute_b32 v139, v109, v140
	s_waitcnt lgkmcnt(14)
	v_add_f32_e32 v168, v168, v167
	s_waitcnt lgkmcnt(13)
	v_add_f32_e32 v166, v166, v165
	s_waitcnt lgkmcnt(12)
	v_add_f32_e32 v164, v164, v163
	s_waitcnt lgkmcnt(11)
	v_add_f32_e32 v162, v162, v161
	s_waitcnt lgkmcnt(10)
	v_add_f32_e32 v159, v159, v157
	s_waitcnt lgkmcnt(9)
	v_add_f32_e32 v158, v158, v156
	s_waitcnt lgkmcnt(8)
	v_add_f32_e32 v152, v152, v150
	s_waitcnt lgkmcnt(7)
	v_add_f32_e32 v160, v160, v149
	s_waitcnt lgkmcnt(6)
	v_add_f32_e32 v153, v153, v151
	s_waitcnt lgkmcnt(5)
	v_add_f32_e32 v155, v155, v154
	s_waitcnt lgkmcnt(4)
	v_add_f32_e32 v148, v148, v147
	s_waitcnt lgkmcnt(3)
	v_add_f32_e32 v146, v146, v145
	s_waitcnt lgkmcnt(2)
	v_add_f32_e32 v142, v142, v141
	s_waitcnt lgkmcnt(1)
	v_add_f32_e32 v144, v144, v143
	s_waitcnt lgkmcnt(0)
	v_add_f32_e32 v140, v140, v139
	ds_bpermute_b32 v167, v111, v168
	ds_bpermute_b32 v165, v111, v166
	ds_bpermute_b32 v163, v111, v164
	ds_bpermute_b32 v161, v111, v162
	ds_bpermute_b32 v157, v111, v159
	ds_bpermute_b32 v156, v111, v158
	ds_bpermute_b32 v150, v111, v152
	ds_bpermute_b32 v149, v111, v160
	ds_bpermute_b32 v151, v111, v153
	ds_bpermute_b32 v154, v111, v155
	ds_bpermute_b32 v147, v111, v148
	ds_bpermute_b32 v145, v111, v146
	ds_bpermute_b32 v141, v111, v142
	ds_bpermute_b32 v143, v111, v144
	ds_bpermute_b32 v139, v111, v140
	s_waitcnt lgkmcnt(14)
	v_add_f32_e32 v168, v168, v167
	s_waitcnt lgkmcnt(13)
	v_add_f32_e32 v166, v166, v165
	s_waitcnt lgkmcnt(12)
	v_add_f32_e32 v164, v164, v163
	s_waitcnt lgkmcnt(11)
	v_add_f32_e32 v162, v162, v161
	s_waitcnt lgkmcnt(10)
	v_add_f32_e32 v159, v159, v157
	s_waitcnt lgkmcnt(9)
	v_add_f32_e32 v158, v158, v156
	s_waitcnt lgkmcnt(8)
	v_add_f32_e32 v152, v152, v150
	s_waitcnt lgkmcnt(7)
	v_add_f32_e32 v160, v160, v149
	s_waitcnt lgkmcnt(6)
	v_add_f32_e32 v153, v153, v151
	s_waitcnt lgkmcnt(5)
	v_add_f32_e32 v155, v155, v154
	s_waitcnt lgkmcnt(4)
	v_add_f32_e32 v148, v148, v147
	s_waitcnt lgkmcnt(3)
	v_add_f32_e32 v146, v146, v145
	s_waitcnt lgkmcnt(2)
	v_add_f32_e32 v142, v142, v141
	s_waitcnt lgkmcnt(1)
	v_add_f32_e32 v144, v144, v143
	s_waitcnt lgkmcnt(0)
	v_add_f32_e32 v140, v140, v139
	ds_bpermute_b32 v167, v113, v168
	ds_bpermute_b32 v165, v113, v166
	ds_bpermute_b32 v163, v113, v164
	ds_bpermute_b32 v161, v113, v162
	ds_bpermute_b32 v157, v113, v159
	ds_bpermute_b32 v156, v113, v158
	ds_bpermute_b32 v150, v113, v152
	ds_bpermute_b32 v149, v113, v160
	ds_bpermute_b32 v151, v113, v153
	ds_bpermute_b32 v154, v113, v155
	ds_bpermute_b32 v147, v113, v148
	ds_bpermute_b32 v145, v113, v146
	ds_bpermute_b32 v141, v113, v142
	ds_bpermute_b32 v143, v113, v144
	ds_bpermute_b32 v139, v113, v140
	s_waitcnt lgkmcnt(14)
	v_add_f32_e32 v168, v168, v167
	s_waitcnt lgkmcnt(13)
	v_add_f32_e32 v166, v166, v165
	s_waitcnt lgkmcnt(12)
	v_add_f32_e32 v164, v164, v163
	s_waitcnt lgkmcnt(11)
	v_add_f32_e32 v162, v162, v161
	s_waitcnt lgkmcnt(10)
	v_add_f32_e32 v159, v159, v157
	s_waitcnt lgkmcnt(9)
	v_add_f32_e32 v158, v158, v156
	s_waitcnt lgkmcnt(8)
	v_add_f32_e32 v152, v152, v150
	s_waitcnt lgkmcnt(7)
	v_add_f32_e32 v160, v160, v149
	s_waitcnt lgkmcnt(6)
	v_add_f32_e32 v153, v153, v151
	s_waitcnt lgkmcnt(5)
	v_add_f32_e32 v155, v155, v154
	s_waitcnt lgkmcnt(4)
	v_add_f32_e32 v148, v148, v147
	s_waitcnt lgkmcnt(3)
	v_add_f32_e32 v146, v146, v145
	s_waitcnt lgkmcnt(2)
	v_add_f32_e32 v142, v142, v141
	s_waitcnt lgkmcnt(1)
	v_add_f32_e32 v144, v144, v143
	s_waitcnt lgkmcnt(0)
	v_add_f32_e32 v140, v140, v139
	ds_bpermute_b32 v167, v115, v168
	ds_bpermute_b32 v165, v115, v166
	ds_bpermute_b32 v163, v115, v164
	ds_bpermute_b32 v161, v115, v162
	ds_bpermute_b32 v157, v115, v159
	ds_bpermute_b32 v156, v115, v158
	ds_bpermute_b32 v150, v115, v152
	ds_bpermute_b32 v149, v115, v160
	ds_bpermute_b32 v151, v115, v153
	ds_bpermute_b32 v154, v115, v155
	ds_bpermute_b32 v147, v115, v148
	ds_bpermute_b32 v145, v115, v146
	ds_bpermute_b32 v141, v115, v142
	ds_bpermute_b32 v143, v115, v144
	ds_bpermute_b32 v139, v115, v140
	s_waitcnt lgkmcnt(14)
	v_add_f32_e32 v168, v168, v167
	s_waitcnt lgkmcnt(13)
	v_add_f32_e32 v166, v166, v165
	s_waitcnt lgkmcnt(12)
	v_add_f32_e32 v164, v164, v163
	s_waitcnt lgkmcnt(11)
	v_add_f32_e32 v162, v162, v161
	s_waitcnt lgkmcnt(10)
	v_add_f32_e32 v159, v159, v157
	s_waitcnt lgkmcnt(9)
	v_add_f32_e32 v158, v158, v156
	s_waitcnt lgkmcnt(8)
	v_add_f32_e32 v152, v152, v150
	s_waitcnt lgkmcnt(7)
	v_add_f32_e32 v160, v160, v149
	s_waitcnt lgkmcnt(6)
	v_add_f32_e32 v153, v153, v151
	s_waitcnt lgkmcnt(5)
	v_add_f32_e32 v155, v155, v154
	s_waitcnt lgkmcnt(4)
	v_add_f32_e32 v148, v148, v147
	s_waitcnt lgkmcnt(3)
	v_add_f32_e32 v146, v146, v145
	s_waitcnt lgkmcnt(2)
	v_add_f32_e32 v142, v142, v141
	s_waitcnt lgkmcnt(1)
	v_add_f32_e32 v144, v144, v143
	s_waitcnt lgkmcnt(0)
	v_add_f32_e32 v140, v140, v139
	ds_bpermute_b32 v167, v116, v168
	ds_bpermute_b32 v165, v116, v166
	ds_bpermute_b32 v163, v116, v164
	ds_bpermute_b32 v161, v116, v162
	ds_bpermute_b32 v157, v116, v159
	ds_bpermute_b32 v156, v116, v158
	ds_bpermute_b32 v150, v116, v152
	ds_bpermute_b32 v149, v116, v160
	ds_bpermute_b32 v151, v116, v153
	ds_bpermute_b32 v154, v116, v155
	ds_bpermute_b32 v147, v116, v148
	ds_bpermute_b32 v145, v116, v146
	ds_bpermute_b32 v141, v116, v142
	ds_bpermute_b32 v143, v116, v144
	ds_bpermute_b32 v139, v116, v140
	s_waitcnt lgkmcnt(14)
	v_add_f32_e32 v168, v168, v167
	s_waitcnt lgkmcnt(13)
	v_add_f32_e32 v166, v166, v165
	s_waitcnt lgkmcnt(12)
	v_add_f32_e32 v164, v164, v163
	s_waitcnt lgkmcnt(11)
	v_add_f32_e32 v162, v162, v161
	s_waitcnt lgkmcnt(10)
	v_add_f32_e32 v159, v159, v157
	s_waitcnt lgkmcnt(9)
	v_add_f32_e32 v158, v158, v156
	s_waitcnt lgkmcnt(8)
	v_add_f32_e32 v152, v152, v150
	s_waitcnt lgkmcnt(7)
	v_add_f32_e32 v160, v160, v149
	s_waitcnt lgkmcnt(6)
	v_add_f32_e32 v153, v153, v151
	s_waitcnt lgkmcnt(5)
	v_add_f32_e32 v155, v155, v154
	s_waitcnt lgkmcnt(4)
	v_add_f32_e32 v148, v148, v147
	s_waitcnt lgkmcnt(3)
	v_add_f32_e32 v146, v146, v145
	s_waitcnt lgkmcnt(2)
	v_add_f32_e32 v142, v142, v141
	s_waitcnt lgkmcnt(1)
	v_add_f32_e32 v144, v144, v143
	s_waitcnt lgkmcnt(0)
	v_add_f32_e32 v140, v140, v139
	s_and_saveexec_b64 s[10:11], vcc
	s_cbranch_execz .Lredux_outproj_1
	v_mov_b32_e32 v37, v1
	v_lshl_add_u64 v[40:41], v[34:35], 0, v[36:37]
	global_store_dword v[40:41], v168, off offset:4
	global_store_dword v[40:41], v166, off offset:8
	global_store_dword v[40:41], v164, off offset:12
	global_store_dword v[40:41], v162, off offset:32
	global_store_dword v[40:41], v159, off offset:36
	global_store_dword v[40:41], v158, off offset:40
	global_store_dword v[40:41], v152, off offset:44
	global_store_dword v[40:41], v160, off offset:64
	global_store_dword v[40:41], v153, off offset:68
	global_store_dword v[40:41], v155, off offset:72
	global_store_dword v[40:41], v148, off offset:76
	global_store_dword v[40:41], v146, off offset:96
	global_store_dword v[40:41], v142, off offset:100
	global_store_dword v[40:41], v144, off offset:104
	global_store_dword v[40:41], v140, off offset:108

.LBB0_297:
	s_or_b64 exec, exec, s[10:11]
	v_mul_f32_e32 v136, v136, v136
	v_fmac_f32_e32 v136, v134, v134
	v_mul_f32_e32 v135, v135, v135
	v_fmac_f32_e32 v135, v133, v133
	v_mul_f32_e32 v130, v130, v130
	v_fmac_f32_e32 v130, v128, v128
	v_mul_f32_e32 v132, v132, v132
	v_fmac_f32_e32 v132, v131, v131
	v_mul_f32_e32 v129, v129, v129
	v_fmac_f32_e32 v129, v127, v127
	v_mul_f32_e32 v125, v125, v125
	v_fmac_f32_e32 v125, v124, v124
	v_mul_f32_e32 v120, v120, v120
	v_fmac_f32_e32 v120, v118, v118
	v_mul_f32_e32 v126, v126, v126
	v_fmac_f32_e32 v126, v117, v117
	v_mul_f32_e32 v121, v121, v121
	v_fmac_f32_e32 v121, v119, v119
	v_mul_f32_e32 v123, v123, v123
	v_fmac_f32_e32 v123, v122, v122
	v_mul_f32_e32 v114, v114, v114
	v_fmac_f32_e32 v114, v112, v112
	v_mul_f32_e32 v108, v108, v108
	v_fmac_f32_e32 v108, v106, v106
	v_mul_f32_e32 v104, v104, v104
	v_fmac_f32_e32 v104, v103, v103
	v_mul_f32_e32 v110, v110, v110
	v_fmac_f32_e32 v110, v102, v102
	s_waitcnt lgkmcnt(0)
	ds_bpermute_b32 v134, v109, v136
	ds_bpermute_b32 v133, v109, v135
	ds_bpermute_b32 v128, v109, v130
	ds_bpermute_b32 v131, v109, v132
	ds_bpermute_b32 v127, v109, v129
	ds_bpermute_b32 v124, v109, v125
	ds_bpermute_b32 v118, v109, v120
	ds_bpermute_b32 v117, v109, v126
	ds_bpermute_b32 v119, v109, v121
	ds_bpermute_b32 v122, v109, v123
	ds_bpermute_b32 v112, v109, v114
	ds_bpermute_b32 v106, v109, v108
	ds_bpermute_b32 v103, v109, v104
	ds_bpermute_b32 v102, v109, v110
	s_waitcnt lgkmcnt(13)
	v_add_f32_e32 v136, v136, v134
	s_waitcnt lgkmcnt(12)
	v_add_f32_e32 v135, v135, v133
	s_waitcnt lgkmcnt(11)
	v_add_f32_e32 v130, v130, v128
	s_waitcnt lgkmcnt(10)
	v_add_f32_e32 v132, v132, v131
	s_waitcnt lgkmcnt(9)
	v_add_f32_e32 v129, v129, v127
	s_waitcnt lgkmcnt(8)
	v_add_f32_e32 v125, v125, v124
	s_waitcnt lgkmcnt(7)
	v_add_f32_e32 v120, v120, v118
	s_waitcnt lgkmcnt(6)
	v_add_f32_e32 v126, v126, v117
	s_waitcnt lgkmcnt(5)
	v_add_f32_e32 v121, v121, v119
	s_waitcnt lgkmcnt(4)
	v_add_f32_e32 v123, v123, v122
	s_waitcnt lgkmcnt(3)
	v_add_f32_e32 v114, v114, v112
	s_waitcnt lgkmcnt(2)
	v_add_f32_e32 v108, v108, v106
	s_waitcnt lgkmcnt(1)
	v_add_f32_e32 v104, v104, v103
	s_waitcnt lgkmcnt(0)
	v_add_f32_e32 v110, v110, v102
	ds_bpermute_b32 v134, v111, v136
	ds_bpermute_b32 v133, v111, v135
	ds_bpermute_b32 v128, v111, v130
	ds_bpermute_b32 v131, v111, v132
	ds_bpermute_b32 v127, v111, v129
	ds_bpermute_b32 v124, v111, v125
	ds_bpermute_b32 v118, v111, v120
	ds_bpermute_b32 v117, v111, v126
	ds_bpermute_b32 v119, v111, v121
	ds_bpermute_b32 v122, v111, v123
	ds_bpermute_b32 v112, v111, v114
	ds_bpermute_b32 v106, v111, v108
	ds_bpermute_b32 v103, v111, v104
	ds_bpermute_b32 v102, v111, v110
	s_waitcnt lgkmcnt(13)
	v_add_f32_e32 v136, v136, v134
	s_waitcnt lgkmcnt(12)
	v_add_f32_e32 v135, v135, v133
	s_waitcnt lgkmcnt(11)
	v_add_f32_e32 v130, v130, v128
	s_waitcnt lgkmcnt(10)
	v_add_f32_e32 v132, v132, v131
	s_waitcnt lgkmcnt(9)
	v_add_f32_e32 v129, v129, v127
	s_waitcnt lgkmcnt(8)
	v_add_f32_e32 v125, v125, v124
	s_waitcnt lgkmcnt(7)
	v_add_f32_e32 v120, v120, v118
	s_waitcnt lgkmcnt(6)
	v_add_f32_e32 v126, v126, v117
	s_waitcnt lgkmcnt(5)
	v_add_f32_e32 v121, v121, v119
	s_waitcnt lgkmcnt(4)
	v_add_f32_e32 v123, v123, v122
	s_waitcnt lgkmcnt(3)
	v_add_f32_e32 v114, v114, v112
	s_waitcnt lgkmcnt(2)
	v_add_f32_e32 v108, v108, v106
	s_waitcnt lgkmcnt(1)
	v_add_f32_e32 v104, v104, v103
	s_waitcnt lgkmcnt(0)
	v_add_f32_e32 v110, v110, v102
	ds_bpermute_b32 v134, v113, v136
	ds_bpermute_b32 v133, v113, v135
	ds_bpermute_b32 v128, v113, v130
	ds_bpermute_b32 v131, v113, v132
	ds_bpermute_b32 v127, v113, v129
	ds_bpermute_b32 v124, v113, v125
	ds_bpermute_b32 v118, v113, v120
	ds_bpermute_b32 v117, v113, v126
	ds_bpermute_b32 v119, v113, v121
	ds_bpermute_b32 v122, v113, v123
	ds_bpermute_b32 v112, v113, v114
	ds_bpermute_b32 v106, v113, v108
	ds_bpermute_b32 v103, v113, v104
	ds_bpermute_b32 v102, v113, v110
	s_waitcnt lgkmcnt(13)
	v_add_f32_e32 v136, v136, v134
	s_waitcnt lgkmcnt(12)
	v_add_f32_e32 v135, v135, v133
	s_waitcnt lgkmcnt(11)
	v_add_f32_e32 v130, v130, v128
	s_waitcnt lgkmcnt(10)
	v_add_f32_e32 v132, v132, v131
	s_waitcnt lgkmcnt(9)
	v_add_f32_e32 v129, v129, v127
	s_waitcnt lgkmcnt(8)
	v_add_f32_e32 v125, v125, v124
	s_waitcnt lgkmcnt(7)
	v_add_f32_e32 v120, v120, v118
	s_waitcnt lgkmcnt(6)
	v_add_f32_e32 v126, v126, v117
	s_waitcnt lgkmcnt(5)
	v_add_f32_e32 v121, v121, v119
	s_waitcnt lgkmcnt(4)
	v_add_f32_e32 v123, v123, v122
	s_waitcnt lgkmcnt(3)
	v_add_f32_e32 v114, v114, v112
	s_waitcnt lgkmcnt(2)
	v_add_f32_e32 v108, v108, v106
	s_waitcnt lgkmcnt(1)
	v_add_f32_e32 v104, v104, v103
	s_waitcnt lgkmcnt(0)
	v_add_f32_e32 v110, v110, v102
	ds_bpermute_b32 v134, v115, v136
	ds_bpermute_b32 v133, v115, v135
	ds_bpermute_b32 v128, v115, v130
	ds_bpermute_b32 v131, v115, v132
	ds_bpermute_b32 v127, v115, v129
	ds_bpermute_b32 v124, v115, v125
	ds_bpermute_b32 v118, v115, v120
	ds_bpermute_b32 v117, v115, v126
	ds_bpermute_b32 v119, v115, v121
	ds_bpermute_b32 v122, v115, v123
	ds_bpermute_b32 v112, v115, v114
	ds_bpermute_b32 v106, v115, v108
	ds_bpermute_b32 v103, v115, v104
	ds_bpermute_b32 v102, v115, v110
	s_waitcnt lgkmcnt(13)
	v_add_f32_e32 v136, v136, v134
	s_waitcnt lgkmcnt(12)
	v_add_f32_e32 v135, v135, v133
	s_waitcnt lgkmcnt(11)
	v_add_f32_e32 v130, v130, v128
	s_waitcnt lgkmcnt(10)
	v_add_f32_e32 v132, v132, v131
	s_waitcnt lgkmcnt(9)
	v_add_f32_e32 v129, v129, v127
	s_waitcnt lgkmcnt(8)
	v_add_f32_e32 v125, v125, v124
	s_waitcnt lgkmcnt(7)
	v_add_f32_e32 v120, v120, v118
	s_waitcnt lgkmcnt(6)
	v_add_f32_e32 v126, v126, v117
	s_waitcnt lgkmcnt(5)
	v_add_f32_e32 v121, v121, v119
	s_waitcnt lgkmcnt(4)
	v_add_f32_e32 v123, v123, v122
	s_waitcnt lgkmcnt(3)
	v_add_f32_e32 v114, v114, v112
	s_waitcnt lgkmcnt(2)
	v_add_f32_e32 v108, v108, v106
	s_waitcnt lgkmcnt(1)
	v_add_f32_e32 v104, v104, v103
	s_waitcnt lgkmcnt(0)
	v_add_f32_e32 v110, v110, v102
	ds_bpermute_b32 v134, v116, v136
	ds_bpermute_b32 v133, v116, v135
	ds_bpermute_b32 v128, v116, v130
	ds_bpermute_b32 v131, v116, v132
	ds_bpermute_b32 v127, v116, v129
	ds_bpermute_b32 v124, v116, v125
	ds_bpermute_b32 v118, v116, v120
	ds_bpermute_b32 v117, v116, v126
	ds_bpermute_b32 v119, v116, v121
	ds_bpermute_b32 v122, v116, v123
	ds_bpermute_b32 v112, v116, v114
	ds_bpermute_b32 v106, v116, v108
	ds_bpermute_b32 v103, v116, v104
	ds_bpermute_b32 v102, v116, v110
	s_waitcnt lgkmcnt(13)
	v_add_f32_e32 v136, v136, v134
	s_waitcnt lgkmcnt(12)
	v_add_f32_e32 v135, v135, v133
	s_waitcnt lgkmcnt(11)
	v_add_f32_e32 v130, v130, v128
	s_waitcnt lgkmcnt(10)
	v_add_f32_e32 v132, v132, v131
	s_waitcnt lgkmcnt(9)
	v_add_f32_e32 v129, v129, v127
	s_waitcnt lgkmcnt(8)
	v_add_f32_e32 v125, v125, v124
	s_waitcnt lgkmcnt(7)
	v_add_f32_e32 v120, v120, v118
	s_waitcnt lgkmcnt(6)
	v_add_f32_e32 v126, v126, v117
	s_waitcnt lgkmcnt(5)
	v_add_f32_e32 v121, v121, v119
	s_waitcnt lgkmcnt(4)
	v_add_f32_e32 v123, v123, v122
	s_waitcnt lgkmcnt(3)
	v_add_f32_e32 v114, v114, v112
	s_waitcnt lgkmcnt(2)
	v_add_f32_e32 v108, v108, v106
	s_waitcnt lgkmcnt(1)
	v_add_f32_e32 v104, v104, v103
	s_waitcnt lgkmcnt(0)
	v_add_f32_e32 v110, v110, v102
	s_and_saveexec_b64 s[10:11], vcc
	s_cbranch_execz .Lredux_outproj_2
	v_mov_b32_e32 v37, v1
	v_lshl_add_u64 v[4:5], v[34:35], 0, v[36:37]
	global_store_dword v[4:5], v136, off offset:132
	global_store_dword v[4:5], v135, off offset:136
	global_store_dword v[4:5], v130, off offset:140
	global_store_dword v[4:5], v132, off offset:160
	global_store_dword v[4:5], v129, off offset:164
	global_store_dword v[4:5], v125, off offset:168
	global_store_dword v[4:5], v120, off offset:172
	global_store_dword v[4:5], v126, off offset:192
	global_store_dword v[4:5], v121, off offset:196
	global_store_dword v[4:5], v123, off offset:200
	global_store_dword v[4:5], v114, off offset:204
	global_store_dword v[4:5], v108, off offset:224
	global_store_dword v[4:5], v104, off offset:228
	global_store_dword v[4:5], v110, off offset:232

.LBB0_2303:
	s_or_b64 exec, exec, s[10:11]
	v_mul_f32_e32 v168, v168, v168
	v_fmac_f32_e32 v168, v167, v167
	v_mul_f32_e32 v166, v166, v166
	v_fmac_f32_e32 v166, v165, v165
	v_mul_f32_e32 v164, v164, v164
	v_fmac_f32_e32 v164, v163, v163
	v_mul_f32_e32 v162, v162, v162
	v_fmac_f32_e32 v162, v161, v161
	v_mul_f32_e32 v157, v157, v157
	v_fmac_f32_e32 v157, v155, v155
	v_mul_f32_e32 v156, v156, v156
	v_fmac_f32_e32 v156, v154, v154
	v_mul_f32_e32 v150, v150, v150
	v_fmac_f32_e32 v150, v148, v148
	v_mul_f32_e32 v158, v158, v158
	v_fmac_f32_e32 v158, v147, v147
	v_mul_f32_e32 v151, v151, v151
	v_fmac_f32_e32 v151, v149, v149
	v_mul_f32_e32 v153, v153, v153
	v_fmac_f32_e32 v153, v152, v152
	v_mul_f32_e32 v146, v146, v146
	v_fmac_f32_e32 v146, v145, v145
	v_mul_f32_e32 v144, v144, v144
	v_fmac_f32_e32 v144, v143, v143
	v_mul_f32_e32 v140, v140, v140
	v_fmac_f32_e32 v140, v139, v139
	v_mul_f32_e32 v142, v142, v142
	v_fmac_f32_e32 v142, v141, v141
	v_mul_f32_e32 v138, v138, v138
	v_fmac_f32_e32 v138, v137, v137
	s_waitcnt lgkmcnt(0)
	ds_bpermute_b32 v167, v108, v168
	ds_bpermute_b32 v165, v108, v166
	ds_bpermute_b32 v163, v108, v164
	ds_bpermute_b32 v161, v108, v162
	ds_bpermute_b32 v155, v108, v157
	ds_bpermute_b32 v154, v108, v156
	ds_bpermute_b32 v148, v108, v150
	ds_bpermute_b32 v147, v108, v158
	ds_bpermute_b32 v149, v108, v151
	ds_bpermute_b32 v152, v108, v153
	ds_bpermute_b32 v145, v108, v146
	ds_bpermute_b32 v143, v108, v144
	ds_bpermute_b32 v139, v108, v140
	ds_bpermute_b32 v141, v108, v142
	ds_bpermute_b32 v137, v108, v138
	s_waitcnt lgkmcnt(14)
	v_add_f32_e32 v168, v168, v167
	s_waitcnt lgkmcnt(13)
	v_add_f32_e32 v166, v166, v165
	s_waitcnt lgkmcnt(12)
	v_add_f32_e32 v164, v164, v163
	s_waitcnt lgkmcnt(11)
	v_add_f32_e32 v162, v162, v161
	s_waitcnt lgkmcnt(10)
	v_add_f32_e32 v157, v157, v155
	s_waitcnt lgkmcnt(9)
	v_add_f32_e32 v156, v156, v154
	s_waitcnt lgkmcnt(8)
	v_add_f32_e32 v150, v150, v148
	s_waitcnt lgkmcnt(7)
	v_add_f32_e32 v158, v158, v147
	s_waitcnt lgkmcnt(6)
	v_add_f32_e32 v151, v151, v149
	s_waitcnt lgkmcnt(5)
	v_add_f32_e32 v153, v153, v152
	s_waitcnt lgkmcnt(4)
	v_add_f32_e32 v146, v146, v145
	s_waitcnt lgkmcnt(3)
	v_add_f32_e32 v144, v144, v143
	s_waitcnt lgkmcnt(2)
	v_add_f32_e32 v140, v140, v139
	s_waitcnt lgkmcnt(1)
	v_add_f32_e32 v142, v142, v141
	s_waitcnt lgkmcnt(0)
	v_add_f32_e32 v138, v138, v137
	ds_bpermute_b32 v167, v110, v168
	ds_bpermute_b32 v165, v110, v166
	ds_bpermute_b32 v163, v110, v164
	ds_bpermute_b32 v161, v110, v162
	ds_bpermute_b32 v155, v110, v157
	ds_bpermute_b32 v154, v110, v156
	ds_bpermute_b32 v148, v110, v150
	ds_bpermute_b32 v147, v110, v158
	ds_bpermute_b32 v149, v110, v151
	ds_bpermute_b32 v152, v110, v153
	ds_bpermute_b32 v145, v110, v146
	ds_bpermute_b32 v143, v110, v144
	ds_bpermute_b32 v139, v110, v140
	ds_bpermute_b32 v141, v110, v142
	ds_bpermute_b32 v137, v110, v138
	s_waitcnt lgkmcnt(14)
	v_add_f32_e32 v168, v168, v167
	s_waitcnt lgkmcnt(13)
	v_add_f32_e32 v166, v166, v165
	s_waitcnt lgkmcnt(12)
	v_add_f32_e32 v164, v164, v163
	s_waitcnt lgkmcnt(11)
	v_add_f32_e32 v162, v162, v161
	s_waitcnt lgkmcnt(10)
	v_add_f32_e32 v157, v157, v155
	s_waitcnt lgkmcnt(9)
	v_add_f32_e32 v156, v156, v154
	s_waitcnt lgkmcnt(8)
	v_add_f32_e32 v150, v150, v148
	s_waitcnt lgkmcnt(7)
	v_add_f32_e32 v158, v158, v147
	s_waitcnt lgkmcnt(6)
	v_add_f32_e32 v151, v151, v149
	s_waitcnt lgkmcnt(5)
	v_add_f32_e32 v153, v153, v152
	s_waitcnt lgkmcnt(4)
	v_add_f32_e32 v146, v146, v145
	s_waitcnt lgkmcnt(3)
	v_add_f32_e32 v144, v144, v143
	s_waitcnt lgkmcnt(2)
	v_add_f32_e32 v140, v140, v139
	s_waitcnt lgkmcnt(1)
	v_add_f32_e32 v142, v142, v141
	s_waitcnt lgkmcnt(0)
	v_add_f32_e32 v138, v138, v137
	ds_bpermute_b32 v167, v112, v168
	ds_bpermute_b32 v165, v112, v166
	ds_bpermute_b32 v163, v112, v164
	ds_bpermute_b32 v161, v112, v162
	ds_bpermute_b32 v155, v112, v157
	ds_bpermute_b32 v154, v112, v156
	ds_bpermute_b32 v148, v112, v150
	ds_bpermute_b32 v147, v112, v158
	ds_bpermute_b32 v149, v112, v151
	ds_bpermute_b32 v152, v112, v153
	ds_bpermute_b32 v145, v112, v146
	ds_bpermute_b32 v143, v112, v144
	ds_bpermute_b32 v139, v112, v140
	ds_bpermute_b32 v141, v112, v142
	ds_bpermute_b32 v137, v112, v138
	s_waitcnt lgkmcnt(14)
	v_add_f32_e32 v168, v168, v167
	s_waitcnt lgkmcnt(13)
	v_add_f32_e32 v166, v166, v165
	s_waitcnt lgkmcnt(12)
	v_add_f32_e32 v164, v164, v163
	s_waitcnt lgkmcnt(11)
	v_add_f32_e32 v162, v162, v161
	s_waitcnt lgkmcnt(10)
	v_add_f32_e32 v157, v157, v155
	s_waitcnt lgkmcnt(9)
	v_add_f32_e32 v156, v156, v154
	s_waitcnt lgkmcnt(8)
	v_add_f32_e32 v150, v150, v148
	s_waitcnt lgkmcnt(7)
	v_add_f32_e32 v158, v158, v147
	s_waitcnt lgkmcnt(6)
	v_add_f32_e32 v151, v151, v149
	s_waitcnt lgkmcnt(5)
	v_add_f32_e32 v153, v153, v152
	s_waitcnt lgkmcnt(4)
	v_add_f32_e32 v146, v146, v145
	s_waitcnt lgkmcnt(3)
	v_add_f32_e32 v144, v144, v143
	s_waitcnt lgkmcnt(2)
	v_add_f32_e32 v140, v140, v139
	s_waitcnt lgkmcnt(1)
	v_add_f32_e32 v142, v142, v141
	s_waitcnt lgkmcnt(0)
	v_add_f32_e32 v138, v138, v137
	ds_bpermute_b32 v167, v113, v168
	ds_bpermute_b32 v165, v113, v166
	ds_bpermute_b32 v163, v113, v164
	ds_bpermute_b32 v161, v113, v162
	ds_bpermute_b32 v155, v113, v157
	ds_bpermute_b32 v154, v113, v156
	ds_bpermute_b32 v148, v113, v150
	ds_bpermute_b32 v147, v113, v158
	ds_bpermute_b32 v149, v113, v151
	ds_bpermute_b32 v152, v113, v153
	ds_bpermute_b32 v145, v113, v146
	ds_bpermute_b32 v143, v113, v144
	ds_bpermute_b32 v139, v113, v140
	ds_bpermute_b32 v141, v113, v142
	ds_bpermute_b32 v137, v113, v138
	s_waitcnt lgkmcnt(14)
	v_add_f32_e32 v168, v168, v167
	s_waitcnt lgkmcnt(13)
	v_add_f32_e32 v166, v166, v165
	s_waitcnt lgkmcnt(12)
	v_add_f32_e32 v164, v164, v163
	s_waitcnt lgkmcnt(11)
	v_add_f32_e32 v162, v162, v161
	s_waitcnt lgkmcnt(10)
	v_add_f32_e32 v157, v157, v155
	s_waitcnt lgkmcnt(9)
	v_add_f32_e32 v156, v156, v154
	s_waitcnt lgkmcnt(8)
	v_add_f32_e32 v150, v150, v148
	s_waitcnt lgkmcnt(7)
	v_add_f32_e32 v158, v158, v147
	s_waitcnt lgkmcnt(6)
	v_add_f32_e32 v151, v151, v149
	s_waitcnt lgkmcnt(5)
	v_add_f32_e32 v153, v153, v152
	s_waitcnt lgkmcnt(4)
	v_add_f32_e32 v146, v146, v145
	s_waitcnt lgkmcnt(3)
	v_add_f32_e32 v144, v144, v143
	s_waitcnt lgkmcnt(2)
	v_add_f32_e32 v140, v140, v139
	s_waitcnt lgkmcnt(1)
	v_add_f32_e32 v142, v142, v141
	s_waitcnt lgkmcnt(0)
	v_add_f32_e32 v138, v138, v137
	ds_bpermute_b32 v167, v115, v168
	ds_bpermute_b32 v165, v115, v166
	ds_bpermute_b32 v163, v115, v164
	ds_bpermute_b32 v161, v115, v162
	ds_bpermute_b32 v155, v115, v157
	ds_bpermute_b32 v154, v115, v156
	ds_bpermute_b32 v148, v115, v150
	ds_bpermute_b32 v147, v115, v158
	ds_bpermute_b32 v149, v115, v151
	ds_bpermute_b32 v152, v115, v153
	ds_bpermute_b32 v145, v115, v146
	ds_bpermute_b32 v143, v115, v144
	ds_bpermute_b32 v139, v115, v140
	ds_bpermute_b32 v141, v115, v142
	ds_bpermute_b32 v137, v115, v138
	s_waitcnt lgkmcnt(14)
	v_add_f32_e32 v168, v168, v167
	s_waitcnt lgkmcnt(13)
	v_add_f32_e32 v166, v166, v165
	s_waitcnt lgkmcnt(12)
	v_add_f32_e32 v164, v164, v163
	s_waitcnt lgkmcnt(11)
	v_add_f32_e32 v162, v162, v161
	s_waitcnt lgkmcnt(10)
	v_add_f32_e32 v157, v157, v155
	s_waitcnt lgkmcnt(9)
	v_add_f32_e32 v156, v156, v154
	s_waitcnt lgkmcnt(8)
	v_add_f32_e32 v150, v150, v148
	s_waitcnt lgkmcnt(7)
	v_add_f32_e32 v158, v158, v147
	s_waitcnt lgkmcnt(6)
	v_add_f32_e32 v151, v151, v149
	s_waitcnt lgkmcnt(5)
	v_add_f32_e32 v153, v153, v152
	s_waitcnt lgkmcnt(4)
	v_add_f32_e32 v146, v146, v145
	s_waitcnt lgkmcnt(3)
	v_add_f32_e32 v144, v144, v143
	s_waitcnt lgkmcnt(2)
	v_add_f32_e32 v140, v140, v139
	s_waitcnt lgkmcnt(1)
	v_add_f32_e32 v142, v142, v141
	s_waitcnt lgkmcnt(0)
	v_add_f32_e32 v138, v138, v137
	s_and_saveexec_b64 s[10:11], vcc
	s_cbranch_execz .Lredux_ffndown_1
	v_lshl_add_u64 v[38:39], v[34:35], 0, v[0:1]
	global_store_dword v[38:39], v168, off offset:4
	global_store_dword v[38:39], v166, off offset:8
	global_store_dword v[38:39], v164, off offset:12
	global_store_dword v[38:39], v162, off offset:32
	global_store_dword v[38:39], v157, off offset:36
	global_store_dword v[38:39], v156, off offset:40
	global_store_dword v[38:39], v150, off offset:44
	global_store_dword v[38:39], v158, off offset:64
	global_store_dword v[38:39], v151, off offset:68
	global_store_dword v[38:39], v153, off offset:72
	global_store_dword v[38:39], v146, off offset:76
	global_store_dword v[38:39], v144, off offset:96
	global_store_dword v[38:39], v140, off offset:100
	global_store_dword v[38:39], v142, off offset:104
	global_store_dword v[38:39], v138, off offset:108

.LBB0_2335:
	s_or_b64 exec, exec, s[10:11]
	v_mul_f32_e32 v134, v134, v134
	v_fmac_f32_e32 v134, v132, v132
	v_mul_f32_e32 v133, v133, v133
	v_fmac_f32_e32 v133, v131, v131
	v_mul_f32_e32 v128, v128, v128
	v_fmac_f32_e32 v128, v126, v126
	v_mul_f32_e32 v130, v130, v130
	v_fmac_f32_e32 v130, v129, v129
	v_mul_f32_e32 v127, v127, v127
	v_fmac_f32_e32 v127, v125, v125
	v_mul_f32_e32 v123, v123, v123
	v_fmac_f32_e32 v123, v122, v122
	v_mul_f32_e32 v118, v118, v118
	v_fmac_f32_e32 v118, v116, v116
	v_mul_f32_e32 v124, v124, v124
	v_fmac_f32_e32 v124, v114, v114
	v_mul_f32_e32 v119, v119, v119
	v_fmac_f32_e32 v119, v117, v117
	v_mul_f32_e32 v121, v121, v121
	v_fmac_f32_e32 v121, v120, v120
	v_mul_f32_e32 v111, v111, v111
	v_fmac_f32_e32 v111, v109, v109
	v_mul_f32_e32 v106, v106, v106
	v_fmac_f32_e32 v106, v104, v104
	v_mul_f32_e32 v102, v102, v102
	v_fmac_f32_e32 v102, v101, v101
	v_mul_f32_e32 v107, v107, v107
	v_fmac_f32_e32 v107, v100, v100
	s_waitcnt lgkmcnt(0)
	ds_bpermute_b32 v132, v108, v134
	ds_bpermute_b32 v131, v108, v133
	ds_bpermute_b32 v126, v108, v128
	ds_bpermute_b32 v129, v108, v130
	ds_bpermute_b32 v125, v108, v127
	ds_bpermute_b32 v122, v108, v123
	ds_bpermute_b32 v116, v108, v118
	ds_bpermute_b32 v114, v108, v124
	ds_bpermute_b32 v117, v108, v119
	ds_bpermute_b32 v120, v108, v121
	ds_bpermute_b32 v109, v108, v111
	ds_bpermute_b32 v104, v108, v106
	ds_bpermute_b32 v101, v108, v102
	ds_bpermute_b32 v100, v108, v107
	s_waitcnt lgkmcnt(13)
	v_add_f32_e32 v134, v134, v132
	s_waitcnt lgkmcnt(12)
	v_add_f32_e32 v133, v133, v131
	s_waitcnt lgkmcnt(11)
	v_add_f32_e32 v128, v128, v126
	s_waitcnt lgkmcnt(10)
	v_add_f32_e32 v130, v130, v129
	s_waitcnt lgkmcnt(9)
	v_add_f32_e32 v127, v127, v125
	s_waitcnt lgkmcnt(8)
	v_add_f32_e32 v123, v123, v122
	s_waitcnt lgkmcnt(7)
	v_add_f32_e32 v118, v118, v116
	s_waitcnt lgkmcnt(6)
	v_add_f32_e32 v124, v124, v114
	s_waitcnt lgkmcnt(5)
	v_add_f32_e32 v119, v119, v117
	s_waitcnt lgkmcnt(4)
	v_add_f32_e32 v121, v121, v120
	s_waitcnt lgkmcnt(3)
	v_add_f32_e32 v111, v111, v109
	s_waitcnt lgkmcnt(2)
	v_add_f32_e32 v106, v106, v104
	s_waitcnt lgkmcnt(1)
	v_add_f32_e32 v102, v102, v101
	s_waitcnt lgkmcnt(0)
	v_add_f32_e32 v107, v107, v100
	ds_bpermute_b32 v132, v110, v134
	ds_bpermute_b32 v131, v110, v133
	ds_bpermute_b32 v126, v110, v128
	ds_bpermute_b32 v129, v110, v130
	ds_bpermute_b32 v125, v110, v127
	ds_bpermute_b32 v122, v110, v123
	ds_bpermute_b32 v116, v110, v118
	ds_bpermute_b32 v114, v110, v124
	ds_bpermute_b32 v117, v110, v119
	ds_bpermute_b32 v120, v110, v121
	ds_bpermute_b32 v109, v110, v111
	ds_bpermute_b32 v104, v110, v106
	ds_bpermute_b32 v101, v110, v102
	ds_bpermute_b32 v100, v110, v107
	s_waitcnt lgkmcnt(13)
	v_add_f32_e32 v134, v134, v132
	s_waitcnt lgkmcnt(12)
	v_add_f32_e32 v133, v133, v131
	s_waitcnt lgkmcnt(11)
	v_add_f32_e32 v128, v128, v126
	s_waitcnt lgkmcnt(10)
	v_add_f32_e32 v130, v130, v129
	s_waitcnt lgkmcnt(9)
	v_add_f32_e32 v127, v127, v125
	s_waitcnt lgkmcnt(8)
	v_add_f32_e32 v123, v123, v122
	s_waitcnt lgkmcnt(7)
	v_add_f32_e32 v118, v118, v116
	s_waitcnt lgkmcnt(6)
	v_add_f32_e32 v124, v124, v114
	s_waitcnt lgkmcnt(5)
	v_add_f32_e32 v119, v119, v117
	s_waitcnt lgkmcnt(4)
	v_add_f32_e32 v121, v121, v120
	s_waitcnt lgkmcnt(3)
	v_add_f32_e32 v111, v111, v109
	s_waitcnt lgkmcnt(2)
	v_add_f32_e32 v106, v106, v104
	s_waitcnt lgkmcnt(1)
	v_add_f32_e32 v102, v102, v101
	s_waitcnt lgkmcnt(0)
	v_add_f32_e32 v107, v107, v100
	ds_bpermute_b32 v132, v112, v134
	ds_bpermute_b32 v131, v112, v133
	ds_bpermute_b32 v126, v112, v128
	ds_bpermute_b32 v129, v112, v130
	ds_bpermute_b32 v125, v112, v127
	ds_bpermute_b32 v122, v112, v123
	ds_bpermute_b32 v116, v112, v118
	ds_bpermute_b32 v114, v112, v124
	ds_bpermute_b32 v117, v112, v119
	ds_bpermute_b32 v120, v112, v121
	ds_bpermute_b32 v109, v112, v111
	ds_bpermute_b32 v104, v112, v106
	ds_bpermute_b32 v101, v112, v102
	ds_bpermute_b32 v100, v112, v107
	s_waitcnt lgkmcnt(13)
	v_add_f32_e32 v134, v134, v132
	s_waitcnt lgkmcnt(12)
	v_add_f32_e32 v133, v133, v131
	s_waitcnt lgkmcnt(11)
	v_add_f32_e32 v128, v128, v126
	s_waitcnt lgkmcnt(10)
	v_add_f32_e32 v130, v130, v129
	s_waitcnt lgkmcnt(9)
	v_add_f32_e32 v127, v127, v125
	s_waitcnt lgkmcnt(8)
	v_add_f32_e32 v123, v123, v122
	s_waitcnt lgkmcnt(7)
	v_add_f32_e32 v118, v118, v116
	s_waitcnt lgkmcnt(6)
	v_add_f32_e32 v124, v124, v114
	s_waitcnt lgkmcnt(5)
	v_add_f32_e32 v119, v119, v117
	s_waitcnt lgkmcnt(4)
	v_add_f32_e32 v121, v121, v120
	s_waitcnt lgkmcnt(3)
	v_add_f32_e32 v111, v111, v109
	s_waitcnt lgkmcnt(2)
	v_add_f32_e32 v106, v106, v104
	s_waitcnt lgkmcnt(1)
	v_add_f32_e32 v102, v102, v101
	s_waitcnt lgkmcnt(0)
	v_add_f32_e32 v107, v107, v100
	ds_bpermute_b32 v132, v113, v134
	ds_bpermute_b32 v131, v113, v133
	ds_bpermute_b32 v126, v113, v128
	ds_bpermute_b32 v129, v113, v130
	ds_bpermute_b32 v125, v113, v127
	ds_bpermute_b32 v122, v113, v123
	ds_bpermute_b32 v116, v113, v118
	ds_bpermute_b32 v114, v113, v124
	ds_bpermute_b32 v117, v113, v119
	ds_bpermute_b32 v120, v113, v121
	ds_bpermute_b32 v109, v113, v111
	ds_bpermute_b32 v104, v113, v106
	ds_bpermute_b32 v101, v113, v102
	ds_bpermute_b32 v100, v113, v107
	s_waitcnt lgkmcnt(13)
	v_add_f32_e32 v134, v134, v132
	s_waitcnt lgkmcnt(12)
	v_add_f32_e32 v133, v133, v131
	s_waitcnt lgkmcnt(11)
	v_add_f32_e32 v128, v128, v126
	s_waitcnt lgkmcnt(10)
	v_add_f32_e32 v130, v130, v129
	s_waitcnt lgkmcnt(9)
	v_add_f32_e32 v127, v127, v125
	s_waitcnt lgkmcnt(8)
	v_add_f32_e32 v123, v123, v122
	s_waitcnt lgkmcnt(7)
	v_add_f32_e32 v118, v118, v116
	s_waitcnt lgkmcnt(6)
	v_add_f32_e32 v124, v124, v114
	s_waitcnt lgkmcnt(5)
	v_add_f32_e32 v119, v119, v117
	s_waitcnt lgkmcnt(4)
	v_add_f32_e32 v121, v121, v120
	s_waitcnt lgkmcnt(3)
	v_add_f32_e32 v111, v111, v109
	s_waitcnt lgkmcnt(2)
	v_add_f32_e32 v106, v106, v104
	s_waitcnt lgkmcnt(1)
	v_add_f32_e32 v102, v102, v101
	s_waitcnt lgkmcnt(0)
	v_add_f32_e32 v107, v107, v100
	ds_bpermute_b32 v132, v115, v134
	ds_bpermute_b32 v131, v115, v133
	ds_bpermute_b32 v126, v115, v128
	ds_bpermute_b32 v129, v115, v130
	ds_bpermute_b32 v125, v115, v127
	ds_bpermute_b32 v122, v115, v123
	ds_bpermute_b32 v116, v115, v118
	ds_bpermute_b32 v114, v115, v124
	ds_bpermute_b32 v117, v115, v119
	ds_bpermute_b32 v120, v115, v121
	ds_bpermute_b32 v109, v115, v111
	ds_bpermute_b32 v104, v115, v106
	ds_bpermute_b32 v101, v115, v102
	ds_bpermute_b32 v100, v115, v107
	s_waitcnt lgkmcnt(13)
	v_add_f32_e32 v134, v134, v132
	s_waitcnt lgkmcnt(12)
	v_add_f32_e32 v133, v133, v131
	s_waitcnt lgkmcnt(11)
	v_add_f32_e32 v128, v128, v126
	s_waitcnt lgkmcnt(10)
	v_add_f32_e32 v130, v130, v129
	s_waitcnt lgkmcnt(9)
	v_add_f32_e32 v127, v127, v125
	s_waitcnt lgkmcnt(8)
	v_add_f32_e32 v123, v123, v122
	s_waitcnt lgkmcnt(7)
	v_add_f32_e32 v118, v118, v116
	s_waitcnt lgkmcnt(6)
	v_add_f32_e32 v124, v124, v114
	s_waitcnt lgkmcnt(5)
	v_add_f32_e32 v119, v119, v117
	s_waitcnt lgkmcnt(4)
	v_add_f32_e32 v121, v121, v120
	s_waitcnt lgkmcnt(3)
	v_add_f32_e32 v111, v111, v109
	s_waitcnt lgkmcnt(2)
	v_add_f32_e32 v106, v106, v104
	s_waitcnt lgkmcnt(1)
	v_add_f32_e32 v102, v102, v101
	s_waitcnt lgkmcnt(0)
	v_add_f32_e32 v107, v107, v100
	s_and_saveexec_b64 s[10:11], vcc
	s_cbranch_execz .Lredux_ffndown_2
	v_lshl_add_u64 v[4:5], v[34:35], 0, v[0:1]
	global_store_dword v[4:5], v134, off offset:132
	global_store_dword v[4:5], v133, off offset:136
	global_store_dword v[4:5], v128, off offset:140
	global_store_dword v[4:5], v130, off offset:160
	global_store_dword v[4:5], v127, off offset:164
	global_store_dword v[4:5], v123, off offset:168
	global_store_dword v[4:5], v118, off offset:172
	global_store_dword v[4:5], v124, off offset:192
	global_store_dword v[4:5], v119, off offset:196
	global_store_dword v[4:5], v121, off offset:200
	global_store_dword v[4:5], v111, off offset:204
	global_store_dword v[4:5], v106, off offset:224
	global_store_dword v[4:5], v102, off offset:228
	global_store_dword v[4:5], v107, off offset:232
